# G1 epilogue: the 14 PROJ dwordx4 stores marked nt (streaming) to keep the A/W operand tiles in L2
# baseline (speedup 1.0000x reference)
; __device__ __forceinline__ u32x4 pack8(const f32x4& a, const f32x4& b) { u32x4 w; w.x = cvt_pk_bf16(a[0], a[1]); w.y = cvt_pk_bf16(a[2], a[3]); w.z = cvt_pk_bf16(b[0], b[1]); w.w = cvt_pk_bf16(b[2], b[3]); return w; }
;     __device__ __forceinline__ void apply(const Ld& d, int row, int c0, int, int, int, const f32x4& a0, const f32x4& b0, const f32x4& a1, const f32x4& b1) const { half(d.g0, row, c0, a0, b0); half(d.g1, row, c0 + 128, a1, b1); }
;     __device__ __forceinline__ void apply(const Ld& d, int row, int c0, int, int, int, const f32x4& a0, const f32x4& b0, const f32x4& a1, const f32x4& b1) const { half(d.g0, d.p0, row, c0, a0, b0); half(d.g1, d.p1, row, c0 + 128, a1, b1); }
;     __device__ __forceinline__ void apply(const Ld& d, int row, int c0, int pn, int wc, int fq, const f32x4& a0, const f32x4& b0, const f32x4& a1, const f32x4& b1) const {
;         const f32x4 t = (d.p[0] + d.p[1]) + (d.p[2] + d.p[3]);
;         const float inv = __builtin_amdgcn_rsqf(((t[0] + t[1]) + (t[2] + t[3])) * (1.f / DM) + EPS);
;         const f32x4 v0 = a0 * inv, v1 = b0 * inv, v2 = a1 * inv, v3 = b1 * inv;
;         if (pn < 18) { *(u32x4*)(proj + (size_t)row * PW + c0) = pack8(v0, v1); *(u32x4*)(proj + (size_t)row * PW + c0 + 128) = pack8(v2, v3); }
;         else if (c0 < 4608 + 32) *(u32x4*)(krope + (size_t)row * 32 + (c0 - 4608)) = pack8(v0, v1);
.LBB0_310:
	s_movk_i32 s44, 0xdc00
	v_ashrrev_i32_e32 v151, 31, v150
	v_pk_mul_f32 v[124:125], v[124:125], v[0:1] op_sel_hi:[1,0]
	v_pk_mul_f32 v[122:123], v[122:123], v[0:1] op_sel_hi:[1,0]
	v_pk_mul_f32 v[120:121], v[120:121], v[0:1] op_sel_hi:[1,0]
	v_pk_mul_f32 v[118:119], v[118:119], v[0:1] op_sel_hi:[1,0]
	s_mov_b32 s45, -1
	s_and_b64 vcc, exec, s[42:43]
	s_cbranch_vccz .LBB0_312
	v_mov_b64_e32 v[158:159], s[74:75]
	v_mad_i64_i32 v[160:161], s[42:43], v152, s29, v[158:159]
	v_cvt_pk_bf16_f32 v126, v130, v131
	v_cvt_pk_bf16_f32 v127, v132, v133
	v_cvt_pk_bf16_f32 v128, v156, v157
	v_cvt_pk_bf16_f32 v129, v154, v155
	v_lshl_add_u64 v[158:159], v[150:151], 1, v[160:161]
	s_mov_b64 s[44:45], 0x100
	s_or_b64 s[22:23], s[22:23], exec
	global_store_dwordx4 v[158:159], v[126:129], off nt
	s_nop 1
	v_cvt_pk_bf16_f32 v126, v122, v123
	v_cvt_pk_bf16_f32 v127, v124, v125
	v_cvt_pk_bf16_f32 v128, v118, v119
	v_cvt_pk_bf16_f32 v129, v120, v121
.LBB0_312:
	s_and_saveexec_b64 s[42:43], s[22:23]
	s_cbranch_execz .LBB0_314
	v_lshl_add_u64 v[158:159], v[150:151], 1, v[160:161]
	v_lshl_add_u64 v[158:159], v[158:159], 0, s[44:45]
	global_store_dwordx4 v[158:159], v[126:129], off nt

; __device__ __forceinline__ u32x4 pack8(const f32x4& a, const f32x4& b) { u32x4 w; w.x = cvt_pk_bf16(a[0], a[1]); w.y = cvt_pk_bf16(a[2], a[3]); w.z = cvt_pk_bf16(b[0], b[1]); w.w = cvt_pk_bf16(b[2], b[3]); return w; }
;     __device__ __forceinline__ void apply(const Ld& d, int row, int c0, int, int, int, const f32x4& a0, const f32x4& b0, const f32x4& a1, const f32x4& b1) const { half(d.g0, row, c0, a0, b0); half(d.g1, row, c0 + 128, a1, b1); }
;     __device__ __forceinline__ void apply(const Ld& d, int row, int c0, int, int, int, const f32x4& a0, const f32x4& b0, const f32x4& a1, const f32x4& b1) const { half(d.g0, d.p0, row, c0, a0, b0); half(d.g1, d.p1, row, c0 + 128, a1, b1); }
;     __device__ __forceinline__ void apply(const Ld& d, int row, int c0, int pn, int wc, int fq, const f32x4& a0, const f32x4& b0, const f32x4& a1, const f32x4& b1) const {
;         const f32x4 t = (d.p[0] + d.p[1]) + (d.p[2] + d.p[3]);
;         const float inv = __builtin_amdgcn_rsqf(((t[0] + t[1]) + (t[2] + t[3])) * (1.f / DM) + EPS);
;         const f32x4 v0 = a0 * inv, v1 = b0 * inv, v2 = a1 * inv, v3 = b1 * inv;
;         if (pn < 18) { *(u32x4*)(proj + (size_t)row * PW + c0) = pack8(v0, v1); *(u32x4*)(proj + (size_t)row * PW + c0 + 128) = pack8(v2, v3); }
;         else if (c0 < 4608 + 32) *(u32x4*)(krope + (size_t)row * 32 + (c0 - 4608)) = pack8(v0, v1);
.LBB0_327:
	s_movk_i32 s78, 0xdc00
	v_pk_mul_f32 v[108:109], v[108:109], v[0:1] op_sel_hi:[1,0]
	v_pk_mul_f32 v[106:107], v[106:107], v[0:1] op_sel_hi:[1,0]
	v_pk_mul_f32 v[104:105], v[104:105], v[0:1] op_sel_hi:[1,0]
	v_pk_mul_f32 v[102:103], v[102:103], v[0:1] op_sel_hi:[1,0]
	s_mov_b32 s79, -1
	s_and_b64 vcc, exec, s[44:45]
	s_cbranch_vccz .LBB0_329
	v_mov_b64_e32 v[124:125], s[74:75]
	v_mad_i64_i32 v[124:125], s[44:45], v118, s29, v[124:125]
	v_cvt_pk_bf16_f32 v110, v114, v115
	v_cvt_pk_bf16_f32 v111, v116, v117
	v_cvt_pk_bf16_f32 v112, v122, v123
	v_cvt_pk_bf16_f32 v113, v120, v121
	v_lshl_add_u64 v[126:127], v[150:151], 1, v[124:125]
	s_mov_b64 s[78:79], 0x100
	s_or_b64 s[0:1], s[0:1], exec
	global_store_dwordx4 v[126:127], v[110:113], off nt
	s_nop 1
	v_cvt_pk_bf16_f32 v110, v106, v107
	v_cvt_pk_bf16_f32 v111, v108, v109
	v_cvt_pk_bf16_f32 v112, v102, v103
	v_cvt_pk_bf16_f32 v113, v104, v105
.LBB0_329:
	s_and_saveexec_b64 s[44:45], s[0:1]
	s_cbranch_execz .LBB0_331
	v_lshl_add_u64 v[124:125], v[150:151], 1, v[124:125]
	v_lshl_add_u64 v[124:125], v[124:125], 0, s[78:79]
	global_store_dwordx4 v[124:125], v[110:113], off nt

; __device__ __forceinline__ u32x4 pack8(const f32x4& a, const f32x4& b) { u32x4 w; w.x = cvt_pk_bf16(a[0], a[1]); w.y = cvt_pk_bf16(a[2], a[3]); w.z = cvt_pk_bf16(b[0], b[1]); w.w = cvt_pk_bf16(b[2], b[3]); return w; }
;     __device__ __forceinline__ void apply(const Ld& d, int row, int c0, int, int, int, const f32x4& a0, const f32x4& b0, const f32x4& a1, const f32x4& b1) const { half(d.g0, row, c0, a0, b0); half(d.g1, row, c0 + 128, a1, b1); }
;     __device__ __forceinline__ void apply(const Ld& d, int row, int c0, int, int, int, const f32x4& a0, const f32x4& b0, const f32x4& a1, const f32x4& b1) const { half(d.g0, d.p0, row, c0, a0, b0); half(d.g1, d.p1, row, c0 + 128, a1, b1); }
;     __device__ __forceinline__ void apply(const Ld& d, int row, int c0, int pn, int wc, int fq, const f32x4& a0, const f32x4& b0, const f32x4& a1, const f32x4& b1) const {
;         const f32x4 t = (d.p[0] + d.p[1]) + (d.p[2] + d.p[3]);
;         const float inv = __builtin_amdgcn_rsqf(((t[0] + t[1]) + (t[2] + t[3])) * (1.f / DM) + EPS);
;         const f32x4 v0 = a0 * inv, v1 = b0 * inv, v2 = a1 * inv, v3 = b1 * inv;
;         if (pn < 18) { *(u32x4*)(proj + (size_t)row * PW + c0) = pack8(v0, v1); *(u32x4*)(proj + (size_t)row * PW + c0 + 128) = pack8(v2, v3); }
;         else if (c0 < 4608 + 32) *(u32x4*)(krope + (size_t)row * 32 + (c0 - 4608)) = pack8(v0, v1);
.LBB0_347:
	v_mov_b64_e32 v[124:125], s[74:75]
	v_mad_i64_i32 v[124:125], s[22:23], v118, s29, v[124:125]
	v_cvt_pk_bf16_f32 v94, v98, v99
	v_cvt_pk_bf16_f32 v95, v100, v101
	v_cvt_pk_bf16_f32 v96, v122, v123
	v_cvt_pk_bf16_f32 v97, v120, v121
	v_lshl_add_u64 v[126:127], v[150:151], 1, v[124:125]
	s_mov_b64 s[78:79], 0x100
	s_or_b64 s[0:1], s[0:1], exec
	global_store_dwordx4 v[126:127], v[94:97], off nt
	s_nop 1
	v_cvt_pk_bf16_f32 v94, v90, v91
	v_cvt_pk_bf16_f32 v95, v92, v93
	v_cvt_pk_bf16_f32 v96, v86, v87
	v_cvt_pk_bf16_f32 v97, v88, v89
	s_and_saveexec_b64 s[22:23], s[0:1]
	s_cbranch_execz .LBB0_346
.LBB0_348:
	v_lshl_add_u64 v[124:125], v[150:151], 1, v[124:125]
	v_lshl_add_u64 v[124:125], v[124:125], 0, s[78:79]
	global_store_dwordx4 v[124:125], v[94:97], off nt
	s_or_b64 exec, exec, s[22:23]
	s_and_b64 vcc, exec, s[44:45]
	s_cbranch_vccnz .LBB0_356

; __device__ __forceinline__ u32x4 pack8(const f32x4& a, const f32x4& b) { u32x4 w; w.x = cvt_pk_bf16(a[0], a[1]); w.y = cvt_pk_bf16(a[2], a[3]); w.z = cvt_pk_bf16(b[0], b[1]); w.w = cvt_pk_bf16(b[2], b[3]); return w; }
;     __device__ __forceinline__ void apply(const Ld& d, int row, int c0, int, int, int, const f32x4& a0, const f32x4& b0, const f32x4& a1, const f32x4& b1) const { half(d.g0, row, c0, a0, b0); half(d.g1, row, c0 + 128, a1, b1); }
;     __device__ __forceinline__ void apply(const Ld& d, int row, int c0, int, int, int, const f32x4& a0, const f32x4& b0, const f32x4& a1, const f32x4& b1) const { half(d.g0, d.p0, row, c0, a0, b0); half(d.g1, d.p1, row, c0 + 128, a1, b1); }
;     __device__ __forceinline__ void apply(const Ld& d, int row, int c0, int pn, int wc, int fq, const f32x4& a0, const f32x4& b0, const f32x4& a1, const f32x4& b1) const {
;         const f32x4 t = (d.p[0] + d.p[1]) + (d.p[2] + d.p[3]);
;         const float inv = __builtin_amdgcn_rsqf(((t[0] + t[1]) + (t[2] + t[3])) * (1.f / DM) + EPS);
;         const f32x4 v0 = a0 * inv, v1 = b0 * inv, v2 = a1 * inv, v3 = b1 * inv;
;         if (pn < 18) { *(u32x4*)(proj + (size_t)row * PW + c0) = pack8(v0, v1); *(u32x4*)(proj + (size_t)row * PW + c0 + 128) = pack8(v2, v3); }
;         else if (c0 < 4608 + 32) *(u32x4*)(krope + (size_t)row * 32 + (c0 - 4608)) = pack8(v0, v1);
.LBB0_364:
	v_mov_b64_e32 v[92:93], s[74:75]
	v_mad_i64_i32 v[92:93], s[22:23], v86, s29, v[92:93]
	v_cvt_pk_bf16_f32 v78, v82, v83
	v_cvt_pk_bf16_f32 v79, v84, v85
	v_cvt_pk_bf16_f32 v80, v90, v91
	v_cvt_pk_bf16_f32 v81, v88, v89
	v_lshl_add_u64 v[94:95], v[150:151], 1, v[92:93]
	s_mov_b64 s[78:79], 0x100
	s_or_b64 s[0:1], s[0:1], exec
	global_store_dwordx4 v[94:95], v[78:81], off nt
	s_nop 1
	v_cvt_pk_bf16_f32 v78, v74, v75
	v_cvt_pk_bf16_f32 v79, v76, v77
	v_cvt_pk_bf16_f32 v80, v70, v71
	v_cvt_pk_bf16_f32 v81, v72, v73
	s_and_saveexec_b64 s[22:23], s[0:1]
	s_cbranch_execz .LBB0_363
.LBB0_365:
	v_lshl_add_u64 v[92:93], v[150:151], 1, v[92:93]
	v_lshl_add_u64 v[92:93], v[92:93], 0, s[78:79]
	global_store_dwordx4 v[92:93], v[78:81], off nt
	s_or_b64 exec, exec, s[22:23]
	s_and_b64 vcc, exec, s[44:45]
	s_cbranch_vccnz .LBB0_373

; __device__ __forceinline__ u32x4 pack8(const f32x4& a, const f32x4& b) { u32x4 w; w.x = cvt_pk_bf16(a[0], a[1]); w.y = cvt_pk_bf16(a[2], a[3]); w.z = cvt_pk_bf16(b[0], b[1]); w.w = cvt_pk_bf16(b[2], b[3]); return w; }
;     __device__ __forceinline__ void apply(const Ld& d, int row, int c0, int, int, int, const f32x4& a0, const f32x4& b0, const f32x4& a1, const f32x4& b1) const { half(d.g0, row, c0, a0, b0); half(d.g1, row, c0 + 128, a1, b1); }
;     __device__ __forceinline__ void apply(const Ld& d, int row, int c0, int, int, int, const f32x4& a0, const f32x4& b0, const f32x4& a1, const f32x4& b1) const { half(d.g0, d.p0, row, c0, a0, b0); half(d.g1, d.p1, row, c0 + 128, a1, b1); }
;     __device__ __forceinline__ void apply(const Ld& d, int row, int c0, int pn, int wc, int fq, const f32x4& a0, const f32x4& b0, const f32x4& a1, const f32x4& b1) const {
;         const f32x4 t = (d.p[0] + d.p[1]) + (d.p[2] + d.p[3]);
;         const float inv = __builtin_amdgcn_rsqf(((t[0] + t[1]) + (t[2] + t[3])) * (1.f / DM) + EPS);
;         const f32x4 v0 = a0 * inv, v1 = b0 * inv, v2 = a1 * inv, v3 = b1 * inv;
;         if (pn < 18) { *(u32x4*)(proj + (size_t)row * PW + c0) = pack8(v0, v1); *(u32x4*)(proj + (size_t)row * PW + c0 + 128) = pack8(v2, v3); }
;         else if (c0 < 4608 + 32) *(u32x4*)(krope + (size_t)row * 32 + (c0 - 4608)) = pack8(v0, v1);
.LBB0_381:
	v_mov_b64_e32 v[94:95], s[74:75]
	v_mad_i64_i32 v[94:95], s[22:23], v86, s29, v[94:95]
	v_cvt_pk_bf16_f32 v62, v66, v67
	v_cvt_pk_bf16_f32 v63, v68, v69
	v_cvt_pk_bf16_f32 v64, v92, v93
	v_cvt_pk_bf16_f32 v65, v90, v91
	v_lshl_add_u64 v[96:97], v[150:151], 1, v[94:95]
	s_mov_b64 s[78:79], 0x100
	s_or_b64 s[0:1], s[0:1], exec
	global_store_dwordx4 v[96:97], v[62:65], off nt
	s_nop 1
	v_cvt_pk_bf16_f32 v62, v58, v59
	v_cvt_pk_bf16_f32 v63, v60, v61
	v_cvt_pk_bf16_f32 v64, v54, v55
	v_cvt_pk_bf16_f32 v65, v56, v57
	s_and_saveexec_b64 s[22:23], s[0:1]
	s_cbranch_execz .LBB0_380
.LBB0_382:
	v_lshl_add_u64 v[94:95], v[150:151], 1, v[94:95]
	v_lshl_add_u64 v[94:95], v[94:95], 0, s[78:79]
	global_store_dwordx4 v[94:95], v[62:65], off nt
	s_or_b64 exec, exec, s[22:23]
	s_and_b64 vcc, exec, s[44:45]
	s_cbranch_vccnz .LBB0_390

; __device__ __forceinline__ u32x4 pack8(const f32x4& a, const f32x4& b) { u32x4 w; w.x = cvt_pk_bf16(a[0], a[1]); w.y = cvt_pk_bf16(a[2], a[3]); w.z = cvt_pk_bf16(b[0], b[1]); w.w = cvt_pk_bf16(b[2], b[3]); return w; }
;     __device__ __forceinline__ void apply(const Ld& d, int row, int c0, int, int, int, const f32x4& a0, const f32x4& b0, const f32x4& a1, const f32x4& b1) const { half(d.g0, row, c0, a0, b0); half(d.g1, row, c0 + 128, a1, b1); }
;     __device__ __forceinline__ void apply(const Ld& d, int row, int c0, int, int, int, const f32x4& a0, const f32x4& b0, const f32x4& a1, const f32x4& b1) const { half(d.g0, d.p0, row, c0, a0, b0); half(d.g1, d.p1, row, c0 + 128, a1, b1); }
;     __device__ __forceinline__ void apply(const Ld& d, int row, int c0, int pn, int wc, int fq, const f32x4& a0, const f32x4& b0, const f32x4& a1, const f32x4& b1) const {
;         const f32x4 t = (d.p[0] + d.p[1]) + (d.p[2] + d.p[3]);
;         const float inv = __builtin_amdgcn_rsqf(((t[0] + t[1]) + (t[2] + t[3])) * (1.f / DM) + EPS);
;         const f32x4 v0 = a0 * inv, v1 = b0 * inv, v2 = a1 * inv, v3 = b1 * inv;
;         if (pn < 18) { *(u32x4*)(proj + (size_t)row * PW + c0) = pack8(v0, v1); *(u32x4*)(proj + (size_t)row * PW + c0 + 128) = pack8(v2, v3); }
;         else if (c0 < 4608 + 32) *(u32x4*)(krope + (size_t)row * 32 + (c0 - 4608)) = pack8(v0, v1);
.LBB0_398:
	v_mov_b64_e32 v[58:59], s[74:75]
	v_mad_i64_i32 v[58:59], s[22:23], v88, s29, v[58:59]
	v_cvt_pk_bf16_f32 v46, v50, v51
	v_cvt_pk_bf16_f32 v47, v52, v53
	v_cvt_pk_bf16_f32 v48, v56, v57
	v_cvt_pk_bf16_f32 v49, v54, v55
	v_lshl_add_u64 v[60:61], v[150:151], 1, v[58:59]
	s_mov_b64 s[78:79], 0x100
	s_or_b64 s[0:1], s[0:1], exec
	global_store_dwordx4 v[60:61], v[46:49], off nt
	s_nop 1
	v_cvt_pk_bf16_f32 v46, v42, v43
	v_cvt_pk_bf16_f32 v47, v44, v45
	v_cvt_pk_bf16_f32 v48, v38, v39
	v_cvt_pk_bf16_f32 v49, v40, v41
	s_and_saveexec_b64 s[22:23], s[0:1]
	s_cbranch_execz .LBB0_397
.LBB0_399:
	v_lshl_add_u64 v[58:59], v[150:151], 1, v[58:59]
	v_lshl_add_u64 v[58:59], v[58:59], 0, s[78:79]
	global_store_dwordx4 v[58:59], v[46:49], off nt
	s_or_b64 exec, exec, s[22:23]
	s_and_b64 vcc, exec, s[44:45]
	s_cbranch_vccnz .LBB0_407

; __device__ __forceinline__ u32x4 pack8(const f32x4& a, const f32x4& b) { u32x4 w; w.x = cvt_pk_bf16(a[0], a[1]); w.y = cvt_pk_bf16(a[2], a[3]); w.z = cvt_pk_bf16(b[0], b[1]); w.w = cvt_pk_bf16(b[2], b[3]); return w; }
;     __device__ __forceinline__ void apply(const Ld& d, int row, int c0, int, int, int, const f32x4& a0, const f32x4& b0, const f32x4& a1, const f32x4& b1) const { half(d.g0, row, c0, a0, b0); half(d.g1, row, c0 + 128, a1, b1); }
;     __device__ __forceinline__ void apply(const Ld& d, int row, int c0, int, int, int, const f32x4& a0, const f32x4& b0, const f32x4& a1, const f32x4& b1) const { half(d.g0, d.p0, row, c0, a0, b0); half(d.g1, d.p1, row, c0 + 128, a1, b1); }
;     __device__ __forceinline__ void apply(const Ld& d, int row, int c0, int pn, int wc, int fq, const f32x4& a0, const f32x4& b0, const f32x4& a1, const f32x4& b1) const {
;         const f32x4 t = (d.p[0] + d.p[1]) + (d.p[2] + d.p[3]);
;         const float inv = __builtin_amdgcn_rsqf(((t[0] + t[1]) + (t[2] + t[3])) * (1.f / DM) + EPS);
;         const f32x4 v0 = a0 * inv, v1 = b0 * inv, v2 = a1 * inv, v3 = b1 * inv;
;         if (pn < 18) { *(u32x4*)(proj + (size_t)row * PW + c0) = pack8(v0, v1); *(u32x4*)(proj + (size_t)row * PW + c0 + 128) = pack8(v2, v3); }
;         else if (c0 < 4608 + 32) *(u32x4*)(krope + (size_t)row * 32 + (c0 - 4608)) = pack8(v0, v1);
.LBB0_415:
	v_mov_b64_e32 v[60:61], s[74:75]
	v_mad_i64_i32 v[60:61], s[22:23], v54, s29, v[60:61]
	v_cvt_pk_bf16_f32 v30, v34, v35
	v_cvt_pk_bf16_f32 v31, v36, v37
	v_cvt_pk_bf16_f32 v32, v58, v59
	v_cvt_pk_bf16_f32 v33, v56, v57
	v_lshl_add_u64 v[62:63], v[150:151], 1, v[60:61]
	s_mov_b64 s[78:79], 0x100
	s_or_b64 s[0:1], s[0:1], exec
	global_store_dwordx4 v[62:63], v[30:33], off nt
	s_nop 1
	v_cvt_pk_bf16_f32 v30, v26, v27
	v_cvt_pk_bf16_f32 v31, v28, v29
	v_cvt_pk_bf16_f32 v32, v22, v23
	v_cvt_pk_bf16_f32 v33, v24, v25
	s_and_saveexec_b64 s[22:23], s[0:1]
	s_cbranch_execz .LBB0_414
.LBB0_416:
	v_lshl_add_u64 v[60:61], v[150:151], 1, v[60:61]
	v_lshl_add_u64 v[60:61], v[60:61], 0, s[78:79]
	global_store_dwordx4 v[60:61], v[30:33], off nt
	s_or_b64 exec, exec, s[22:23]
	s_and_b64 vcc, exec, s[44:45]
	s_cbranch_vccnz .LBB0_424
